# HGRN prep: the lane's four KDT values written with one ds_write_b64 (3 fewer LDS writes, 2 fewer conversions per step) (v58 + kdtpack)
# speedup vs baseline: 1.0024x; 1.0024x over previous
.LBB0_947:
	v_lshlrev_b32_e32 v0, 16, v45
	v_mul_f32_e32 v0, 0xbfb8aa3b, v0
	v_exp_f32_e32 v0, v0
	v_lshlrev_b32_e32 v1, 16, v44
	s_sub_i32 s80, 0, s62
	v_lshlrev_b32_e32 v42, 16, v42
	v_min_f32_e32 v0, 0x7149f2ca, v0
	v_add_f32_e32 v2, 1.0, v0
	v_rcp_f32_e32 v44, v2
	v_fma_f32 v0, v183, v0, 1.0
	v_rcp_f32_e32 v184, v0
	v_lshlrev_b32_e32 v40, 16, v40
	v_mul_f32_e32 v45, v0, v44
	v_fma_f32 v44, -v0, v44, 1.0
	v_lshlrev_b32_e32 v0, 16, v43
	v_mul_f32_e32 v0, 0xbfb8aa3b, v0
	v_exp_f32_e32 v0, v0
	v_cndmask_b32_e64 v184, v184, 1.0, s[58:59]
	v_mul_f32_e32 v2, v2, v184
	v_lshlrev_b32_e32 v38, 16, v38
	v_min_f32_e32 v0, 0x7149f2ca, v0
	v_add_f32_e32 v43, 1.0, v0
	v_rcp_f32_e32 v184, v43
	v_fma_f32 v0, v183, v0, 1.0
	v_rcp_f32_e32 v186, v0
	v_mul_f32_e32 v185, v0, v184
	v_fma_f32 v184, -v0, v184, 1.0
	v_lshlrev_b32_e32 v0, 16, v41
	v_mul_f32_e32 v0, 0xbfb8aa3b, v0
	v_exp_f32_e32 v0, v0
	v_cndmask_b32_e64 v186, v186, 1.0, s[58:59]
	v_mul_f32_e32 v43, v43, v186
	v_mul_f32_e32 v185, v45, v185
	v_min_f32_e32 v0, 0x7149f2ca, v0
	v_add_f32_e32 v41, 1.0, v0
	v_rcp_f32_e32 v186, v41
	v_fma_f32 v0, v183, v0, 1.0
	v_rcp_f32_e32 v188, v0
	v_mul_f32_e32 v43, v2, v43
	v_mul_f32_e32 v187, v0, v186
	v_fma_f32 v186, -v0, v186, 1.0
	v_lshlrev_b32_e32 v0, 16, v39
	v_mul_f32_e32 v0, 0xbfb8aa3b, v0
	v_exp_f32_e32 v0, v0
	v_cndmask_b32_e64 v188, v188, 1.0, s[58:59]
	v_mul_f32_e32 v41, v41, v188
	v_mul_f32_e32 v187, v185, v187
	v_min_f32_e32 v0, 0x7149f2ca, v0
	v_add_f32_e32 v39, 1.0, v0
	v_fma_f32 v0, v183, v0, 1.0
	v_rcp_f32_e32 v188, v39
	v_rcp_f32_e32 v190, v0
	v_mul_f32_e32 v41, v43, v41
	v_mul_f32_e32 v189, v0, v188
	v_cndmask_b32_e64 v190, v190, 1.0, s[58:59]
	v_mul_f32_e32 v39, v39, v190
	v_mul_f32_e32 v189, v187, v189
	v_fma_f32 v188, -v0, v188, 1.0
	v_mul_f32_e32 v39, v41, v39
	ds_bpermute_b32 v0, v57, v189
	ds_bpermute_b32 v190, v57, v39
	s_waitcnt lgkmcnt(1)
	v_mul_f32_e32 v0, v189, v0
	v_cndmask_b32_e64 v0, v189, v0, s[40:41]
	s_waitcnt lgkmcnt(0)
	v_mul_f32_e32 v190, v39, v190
	v_cndmask_b32_e64 v190, v39, v190, s[40:41]
	ds_bpermute_b32 v191, v59, v0
	ds_bpermute_b32 v192, v59, v190
	s_waitcnt lgkmcnt(1)
	v_mul_f32_e32 v191, v0, v191
	v_cndmask_b32_e64 v0, v0, v191, s[42:43]
	s_waitcnt lgkmcnt(0)
	v_mul_f32_e32 v191, v190, v192
	v_cndmask_b32_e64 v190, v190, v191, s[42:43]
	ds_bpermute_b32 v190, v57, v190
	ds_bpermute_b32 v191, v57, v0
	ds_bpermute_b32 v0, v61, v0
	s_waitcnt lgkmcnt(2)
	v_cndmask_b32_e64 v190, 1.0, v190, s[40:41]
	v_mul_f32_e32 v2, v2, v190
	s_waitcnt lgkmcnt(1)
	v_cndmask_b32_e64 v191, 1.0, v191, s[40:41]
	v_min_f32_e32 v2, 0x799a130c, v2
	v_mul_f32_e32 v2, v44, v2
	v_mul_f32_e32 v44, v45, v191
	v_mul_f32_e32 v1, v44, v1
	v_cvt_pk_bf16_f32 v1, v1, s0
	v_lshl_add_u32 v44, v140, 1, s80
	ds_write_b16 v44, v1 offset:22528
	v_cvt_pk_bf16_f32 v1, v2, s0
	ds_write_b16 v44, v1 offset:26880
	s_waitcnt lgkmcnt(2)
	v_mul_f32_e32 v208, v2, v0
	v_lshlrev_b32_e32 v2, 1, v54
	v_add3_u32 v2, s80, v63, v2
	v_mul_f32_e32 v1, v43, v190
	v_mul_f32_e32 v43, v185, v191
	v_min_f32_e32 v1, 0x799a130c, v1
	v_mul_f32_e32 v42, v43, v42
	v_mul_f32_e32 v1, v184, v1
	v_cvt_pk_bf16_f32 v42, v42, s0
	v_lshl_add_u32 v43, v140, 1, s80
	ds_write_b16 v43, v42 offset:22800
	v_cvt_pk_bf16_f32 v42, v1, s0
	v_mul_f32_e32 v209, v1, v0
	ds_write_b16 v43, v42 offset:27152
	v_mul_f32_e32 v1, v41, v190
	v_mul_f32_e32 v41, v187, v191
	v_min_f32_e32 v1, 0x799a130c, v1
	v_mul_f32_e32 v40, v41, v40
	v_mul_f32_e32 v1, v186, v1
	v_cvt_pk_bf16_f32 v40, v40, s0
	v_lshl_add_u32 v41, v140, 1, s80
	ds_write_b16 v41, v40 offset:23072
	v_cvt_pk_bf16_f32 v40, v1, s0
	v_mul_f32_e32 v210, v1, v0
	ds_write_b16 v41, v40 offset:27424
	v_mul_f32_e32 v1, v39, v190
	v_mul_f32_e32 v39, v189, v191
	v_min_f32_e32 v1, 0x799a130c, v1
	v_mul_f32_e32 v38, v39, v38
	v_mul_f32_e32 v1, v188, v1
	v_cvt_pk_bf16_f32 v38, v38, s0
	v_lshl_add_u32 v39, v140, 1, s80
	ds_write_b16 v39, v38 offset:23344
	v_cvt_pk_bf16_f32 v38, v1, s0
	v_mul_f32_e32 v211, v1, v0
	ds_write_b16 v39, v38 offset:27696
	v_cvt_pk_bf16_f32 v212, v208, v209
	v_cvt_pk_bf16_f32 v213, v210, v211
	ds_write_b64 v2, v[212:213] offset:31232
	s_and_saveexec_b64 s[12:13], s[44:45]
	v_lshl_add_u32 v1, v52, 2, s80
	ds_write_b32 v1, v0 offset:43520
	s_or_b64 exec, exec, s[12:13]
	v_lshl_add_u32 v0, v67, 1, s80
	ds_write_b16 v0, v36 offset:37376
	ds_write_b16_d16_hi v0, v36 offset:37424
	ds_write_b16 v0, v37 offset:37472
	ds_write_b16_d16_hi v0, v37 offset:37520

.LBB0_982:
	v_lshlrev_b32_e32 v43, 16, v205
	v_mul_f32_e32 v43, 0xbfb8aa3b, v43
	v_exp_f32_e32 v43, v43
	v_lshlrev_b32_e32 v44, 16, v206
	s_sub_i32 s83, 0, s82
	v_min_f32_e32 v43, 0x7149f2ca, v43
	v_add_f32_e32 v45, 1.0, v43
	v_rcp_f32_e32 v46, v45
	v_fma_f32 v43, v183, v43, 1.0
	v_rcp_f32_e32 v48, v43
	v_mul_f32_e32 v47, v43, v46
	v_fma_f32 v46, -v43, v46, 1.0
	v_lshlrev_b32_e32 v43, 16, v203
	v_mul_f32_e32 v43, 0xbfb8aa3b, v43
	v_exp_f32_e32 v43, v43
	v_cndmask_b32_e64 v48, v48, 1.0, s[56:57]
	v_mul_f32_e32 v45, v45, v48
	v_lshlrev_b32_e32 v48, 16, v204
	v_min_f32_e32 v43, 0x7149f2ca, v43
	v_add_f32_e32 v49, 1.0, v43
	v_rcp_f32_e32 v184, v49
	v_fma_f32 v43, v183, v43, 1.0
	v_rcp_f32_e32 v186, v43
	v_mul_f32_e32 v185, v43, v184
	v_fma_f32 v184, -v43, v184, 1.0
	v_lshlrev_b32_e32 v43, 16, v201
	v_mul_f32_e32 v43, 0xbfb8aa3b, v43
	v_exp_f32_e32 v43, v43
	v_cndmask_b32_e64 v186, v186, 1.0, s[56:57]
	v_mul_f32_e32 v49, v49, v186
	v_mul_f32_e32 v185, v47, v185
	v_min_f32_e32 v43, 0x7149f2ca, v43
	v_add_f32_e32 v187, 1.0, v43
	v_rcp_f32_e32 v188, v187
	v_fma_f32 v43, v183, v43, 1.0
	v_rcp_f32_e32 v190, v43
	v_mul_f32_e32 v49, v45, v49
	v_mul_f32_e32 v189, v43, v188
	v_fma_f32 v188, -v43, v188, 1.0
	v_lshlrev_b32_e32 v43, 16, v199
	v_mul_f32_e32 v43, 0xbfb8aa3b, v43
	v_exp_f32_e32 v43, v43
	v_cndmask_b32_e64 v190, v190, 1.0, s[56:57]
	v_mul_f32_e32 v187, v187, v190
	v_mul_f32_e32 v189, v185, v189
	v_min_f32_e32 v43, 0x7149f2ca, v43
	v_add_f32_e32 v191, 1.0, v43
	v_fma_f32 v43, v183, v43, 1.0
	v_rcp_f32_e32 v192, v191
	v_rcp_f32_e32 v194, v43
	v_mul_f32_e32 v187, v49, v187
	v_lshlrev_b32_e32 v186, 16, v202
	v_mul_f32_e32 v193, v43, v192
	v_cndmask_b32_e64 v194, v194, 1.0, s[56:57]
	v_mul_f32_e32 v191, v191, v194
	v_mul_f32_e32 v193, v189, v193
	v_fma_f32 v192, -v43, v192, 1.0
	v_mul_f32_e32 v191, v187, v191
	ds_bpermute_b32 v43, v57, v193
	ds_bpermute_b32 v194, v57, v191
	v_lshlrev_b32_e32 v190, 16, v200
	s_waitcnt lgkmcnt(1)
	v_mul_f32_e32 v43, v193, v43
	v_cndmask_b32_e64 v43, v193, v43, s[40:41]
	s_waitcnt lgkmcnt(0)
	v_mul_f32_e32 v194, v191, v194
	v_cndmask_b32_e64 v194, v191, v194, s[40:41]
	ds_bpermute_b32 v195, v59, v43
	ds_bpermute_b32 v196, v59, v194
	s_waitcnt lgkmcnt(1)
	v_mul_f32_e32 v195, v43, v195
	v_cndmask_b32_e64 v43, v43, v195, s[42:43]
	s_waitcnt lgkmcnt(0)
	v_mul_f32_e32 v195, v194, v196
	v_cndmask_b32_e64 v194, v194, v195, s[42:43]
	ds_bpermute_b32 v194, v57, v194
	ds_bpermute_b32 v195, v57, v43
	ds_bpermute_b32 v43, v61, v43
	s_waitcnt lgkmcnt(2)
	v_cndmask_b32_e64 v194, 1.0, v194, s[40:41]
	v_mul_f32_e32 v45, v45, v194
	s_waitcnt lgkmcnt(1)
	v_cndmask_b32_e64 v195, 1.0, v195, s[40:41]
	v_min_f32_e32 v45, 0x799a130c, v45
	v_mul_f32_e32 v45, v46, v45
	v_mul_f32_e32 v46, v47, v195
	v_mul_f32_e32 v44, v46, v44
	v_cvt_pk_bf16_f32 v44, v44, s0
	v_lshl_add_u32 v46, v140, 1, s83
	ds_write_b16 v46, v44 offset:22528
	v_cvt_pk_bf16_f32 v44, v45, s0
	ds_write_b16 v46, v44 offset:26880
	s_waitcnt lgkmcnt(2)
	v_mul_f32_e32 v208, v45, v43
	v_lshlrev_b32_e32 v45, 1, v54
	v_add3_u32 v45, s83, v63, v45
	v_mul_f32_e32 v44, v49, v194
	v_mul_f32_e32 v46, v185, v195
	v_min_f32_e32 v44, 0x799a130c, v44
	v_mul_f32_e32 v46, v46, v48
	v_mul_f32_e32 v44, v184, v44
	v_cvt_pk_bf16_f32 v46, v46, s0
	v_lshl_add_u32 v47, v140, 1, s83
	ds_write_b16 v47, v46 offset:22800
	v_cvt_pk_bf16_f32 v46, v44, s0
	v_mul_f32_e32 v209, v44, v43
	ds_write_b16 v47, v46 offset:27152
	v_mul_f32_e32 v44, v187, v194
	v_mul_f32_e32 v46, v189, v195
	v_min_f32_e32 v44, 0x799a130c, v44
	v_mul_f32_e32 v46, v46, v186
	v_mul_f32_e32 v44, v188, v44
	v_cvt_pk_bf16_f32 v46, v46, s0
	v_lshl_add_u32 v47, v140, 1, s83
	ds_write_b16 v47, v46 offset:23072
	v_cvt_pk_bf16_f32 v46, v44, s0
	v_mul_f32_e32 v210, v44, v43
	ds_write_b16 v47, v46 offset:27424
	v_mul_f32_e32 v44, v191, v194
	v_mul_f32_e32 v46, v193, v195
	v_min_f32_e32 v44, 0x799a130c, v44
	v_mul_f32_e32 v46, v46, v190
	v_mul_f32_e32 v44, v192, v44
	v_cvt_pk_bf16_f32 v46, v46, s0
	v_lshl_add_u32 v47, v140, 1, s83
	ds_write_b16 v47, v46 offset:23344
	v_cvt_pk_bf16_f32 v46, v44, s0
	v_mul_f32_e32 v211, v44, v43
	ds_write_b16 v47, v46 offset:27696
	v_cvt_pk_bf16_f32 v212, v208, v209
	v_cvt_pk_bf16_f32 v213, v210, v211
	ds_write_b64 v45, v[212:213] offset:31232
	s_and_saveexec_b64 s[14:15], s[44:45]
	v_lshl_add_u32 v44, v52, 2, s83
	ds_write_b32 v44, v43 offset:43520
	s_or_b64 exec, exec, s[14:15]
	v_lshl_add_u32 v43, v67, 1, s83
	ds_write_b16 v43, v148 offset:37376
	ds_write_b16_d16_hi v43, v148 offset:37424
	ds_write_b16 v43, v149 offset:37472
	ds_write_b16_d16_hi v43, v149 offset:37520
